# MLP-up epilogue: hoist 8 row-stat loads to epilogue top, drop per-step vmcnt(0) drains
# baseline (speedup 1.0000x reference)
.LBB0_711:
	v_lshl_add_u32 v146, s84, 8, v1
	s_cmp_lt_i32 s84, 32
	s_cselect_b64 s[8:9], -1, 0
	v_ashrrev_i32_e32 v147, 31, v146
	v_readlane_b32 s64, v255, 12
	s_mov_b64 s[84:85], -1
	s_and_b64 vcc, exec, s[8:9]
	v_lshl_add_u64 v[150:151], v[146:147], 2, s[6:7]
	v_readlane_b32 s65, v255, 13
	s_cbranch_vccz .LBB0_713
	global_load_dword v214, v[150:151], off
	global_load_dword v215, v[150:151], off offset:64
	global_load_dword v216, v[150:151], off offset:128
	global_load_dword v217, v[150:151], off offset:192
	global_load_dword v218, v[150:151], off offset:512
	global_load_dword v219, v[150:151], off offset:576
	global_load_dword v220, v[150:151], off offset:640
	global_load_dword v221, v[150:151], off offset:704
	s_waitcnt vmcnt(0)
	v_mov_b32_e32 v155, v214
	s_mov_b64 s[84:85], 0

.LBB0_715:
	v_fmamk_f32 v155, v155, 0x3a000000, v205
	v_cmp_gt_f32_e32 vcc, s12, v155
	v_mul_f32_e32 v156, 0x4b800000, v155
	v_lshl_or_b32 v148, s40, 8, v153
	v_cndmask_b32_e32 v155, v155, v156, vcc
	v_rsq_f32_e32 v155, v155
	v_lshlrev_b64 v[158:159], 14, v[146:147]
	v_ashrrev_i32_e32 v149, 31, v148
	v_lshl_add_u64 v[158:159], s[10:11], 0, v[158:159]
	v_mul_f32_e32 v156, 0x45800000, v155
	v_cndmask_b32_e32 v156, v155, v156, vcc
	v_pk_mul_f32 v[128:129], v[128:129], v[156:157] op_sel_hi:[1,0]
	v_pk_mul_f32 v[132:133], v[132:133], v[156:157] op_sel_hi:[1,0]
	v_pk_mul_f32 v[130:131], v[130:131], v[156:157] op_sel_hi:[1,0]
	v_max_f32_e32 v128, 0, v128
	v_pk_mul_f32 v[134:135], v[134:135], v[156:157] op_sel_hi:[1,0]
	v_mul_f32_e32 v147, v128, v128
	v_max_f32_e32 v128, 0, v133
	v_max_f32_e32 v129, 0, v129
	v_max_f32_e32 v130, 0, v130
	v_max_f32_e32 v132, 0, v132
	v_mul_f32_e32 v128, v128, v128
	v_mul_f32_e32 v133, v129, v129
	v_max_f32_e32 v129, 0, v134
	v_mul_f32_e32 v134, v130, v130
	v_max_f32_e32 v130, 0, v135
	v_max_f32_e32 v131, 0, v131
	v_pk_mul_f32 v[120:121], v[120:121], v[156:157] op_sel_hi:[1,0]
	v_lshl_add_u64 v[158:159], v[148:149], 1, v[158:159]
	v_mul_f32_e32 v132, v132, v132
	v_mul_f32_e32 v129, v129, v129
	v_mul_f32_e32 v130, v130, v130
	v_mul_f32_e32 v131, v131, v131
	v_cvt_pk_bf16_f32 v128, v132, v128
	v_pk_mul_f32 v[124:125], v[124:125], v[156:157] op_sel_hi:[1,0]
	v_pk_mul_f32 v[122:123], v[122:123], v[156:157] op_sel_hi:[1,0]
	v_max_f32_e32 v120, 0, v120
	v_cvt_pk_bf16_f32 v129, v129, v130
	v_cvt_pk_bf16_f32 v130, v147, v133
	v_cvt_pk_bf16_f32 v131, v134, v131
	global_store_dwordx4 v[158:159], v[128:131], off
	v_pk_mul_f32 v[126:127], v[126:127], v[156:157] op_sel_hi:[1,0]
	v_max_f32_e32 v121, 0, v121
	v_mul_f32_e32 v128, v120, v120
	v_max_f32_e32 v120, 0, v125
	v_max_f32_e32 v122, 0, v122
	v_max_f32_e32 v124, 0, v124
	v_mul_f32_e32 v120, v120, v120
	v_mul_f32_e32 v125, v121, v121
	v_max_f32_e32 v121, 0, v126
	v_mul_f32_e32 v126, v122, v122
	v_max_f32_e32 v122, 0, v127
	v_max_f32_e32 v123, 0, v123
	v_mul_f32_e32 v124, v124, v124
	v_mul_f32_e32 v121, v121, v121
	v_mul_f32_e32 v122, v122, v122
	v_mul_f32_e32 v123, v123, v123
	v_cvt_pk_bf16_f32 v120, v124, v120
	v_cvt_pk_bf16_f32 v121, v121, v122
	v_cvt_pk_bf16_f32 v122, v128, v125
	v_cvt_pk_bf16_f32 v123, v126, v123
	global_store_dwordx4 v[158:159], v[120:123], off offset:256
	v_readlane_b32 s92, v255, 14
	s_mov_b64 s[84:85], -1
	v_cndmask_b32_e64 v120, 0, 1, s[8:9]
	v_cmp_ne_u32_e64 s[40:41], 1, v120
	s_andn2_b64 vcc, exec, s[8:9]
	v_readlane_b32 s93, v255, 15
	s_cbranch_vccnz .LBB0_717
	s_nop 1
	v_mov_b32_e32 v122, v215
	s_mov_b64 s[84:85], 0

.LBB0_719:
	v_fmamk_f32 v122, v122, 0x3a000000, v205
	v_mul_f32_e32 v123, 0x4b800000, v122
	v_cmp_gt_f32_e32 vcc, s12, v122
	v_lshlrev_b64 v[120:121], 14, v[120:121]
	v_lshl_add_u64 v[120:121], s[10:11], 0, v[120:121]
	v_cndmask_b32_e32 v122, v122, v123, vcc
	v_rsq_f32_e32 v122, v122
	v_lshl_add_u64 v[120:121], v[148:149], 1, v[120:121]
	s_mov_b64 s[8:9], -1
	v_mul_f32_e32 v123, 0x45800000, v122
	v_cndmask_b32_e32 v122, v122, v123, vcc
	v_pk_mul_f32 v[106:107], v[106:107], v[122:123] op_sel_hi:[1,0]
	v_pk_mul_f32 v[116:117], v[116:117], v[122:123] op_sel_hi:[1,0]
	v_pk_mul_f32 v[108:109], v[108:109], v[122:123] op_sel_hi:[1,0]
	v_max_f32_e32 v106, 0, v106
	v_pk_mul_f32 v[118:119], v[118:119], v[122:123] op_sel_hi:[1,0]
	v_mul_f32_e32 v123, v106, v106
	v_max_f32_e32 v106, 0, v117
	v_max_f32_e32 v107, 0, v107
	v_max_f32_e32 v108, 0, v108
	v_max_f32_e32 v116, 0, v116
	v_mul_f32_e32 v106, v106, v106
	v_mul_f32_e32 v117, v107, v107
	v_max_f32_e32 v107, 0, v118
	v_mul_f32_e32 v118, v108, v108
	v_max_f32_e32 v108, 0, v119
	v_max_f32_e32 v109, 0, v109
	v_pk_mul_f32 v[100:101], v[100:101], v[122:123] op_sel_hi:[1,0]
	v_pk_mul_f32 v[98:99], v[98:99], v[122:123] op_sel_hi:[1,0]
	v_mul_f32_e32 v116, v116, v116
	v_mul_f32_e32 v107, v107, v107
	v_mul_f32_e32 v108, v108, v108
	v_mul_f32_e32 v109, v109, v109
	v_cvt_pk_bf16_f32 v106, v116, v106
	v_pk_mul_f32 v[104:105], v[104:105], v[122:123] op_sel_hi:[1,0]
	v_pk_mul_f32 v[102:103], v[102:103], v[122:123] op_sel_hi:[1,0]
	v_max_f32_e32 v98, 0, v98
	v_max_f32_e32 v99, 0, v99
	v_max_f32_e32 v100, 0, v100
	v_cvt_pk_bf16_f32 v107, v107, v108
	v_cvt_pk_bf16_f32 v108, v123, v117
	v_cvt_pk_bf16_f32 v109, v118, v109
	global_store_dwordx4 v[120:121], v[106:109], off
	v_max_f32_e32 v102, 0, v102
	v_max_f32_e32 v101, 0, v101
	v_mul_f32_e32 v106, v98, v98
	v_max_f32_e32 v98, 0, v103
	v_mul_f32_e32 v103, v99, v99
	v_max_f32_e32 v99, 0, v104
	v_mul_f32_e32 v104, v100, v100
	v_max_f32_e32 v100, 0, v105
	v_mul_f32_e32 v98, v98, v98
	v_mul_f32_e32 v99, v99, v99
	v_mul_f32_e32 v100, v100, v100
	v_mul_f32_e32 v102, v102, v102
	v_mul_f32_e32 v101, v101, v101
	v_cvt_pk_bf16_f32 v98, v102, v98
	v_cvt_pk_bf16_f32 v99, v99, v100
	v_cvt_pk_bf16_f32 v100, v106, v103
	s_and_b64 vcc, exec, s[40:41]
	v_cvt_pk_bf16_f32 v101, v104, v101
	global_store_dwordx4 v[120:121], v[98:101], off offset:256
	s_cbranch_vccnz .LBB0_721
	s_nop 1
	v_mov_b32_e32 v100, v216
	s_mov_b64 s[8:9], 0

.LBB0_723:
	v_fmamk_f32 v100, v100, 0x3a000000, v205
	v_mul_f32_e32 v101, 0x4b800000, v100
	v_cmp_gt_f32_e32 vcc, s12, v100
	v_lshlrev_b64 v[98:99], 14, v[98:99]
	v_lshl_add_u64 v[98:99], s[10:11], 0, v[98:99]
	v_cndmask_b32_e32 v100, v100, v101, vcc
	v_rsq_f32_e32 v100, v100
	v_lshl_add_u64 v[98:99], v[148:149], 1, v[98:99]
	s_mov_b64 s[8:9], -1
	v_mul_f32_e32 v101, 0x45800000, v100
	v_cndmask_b32_e32 v100, v100, v101, vcc
	v_pk_mul_f32 v[90:91], v[90:91], v[100:101] op_sel_hi:[1,0]
	v_pk_mul_f32 v[94:95], v[94:95], v[100:101] op_sel_hi:[1,0]
	v_pk_mul_f32 v[92:93], v[92:93], v[100:101] op_sel_hi:[1,0]
	v_max_f32_e32 v90, 0, v90
	v_pk_mul_f32 v[96:97], v[96:97], v[100:101] op_sel_hi:[1,0]
	v_mul_f32_e32 v101, v90, v90
	v_max_f32_e32 v90, 0, v95
	v_max_f32_e32 v91, 0, v91
	v_max_f32_e32 v92, 0, v92
	v_max_f32_e32 v94, 0, v94
	v_mul_f32_e32 v90, v90, v90
	v_mul_f32_e32 v95, v91, v91
	v_max_f32_e32 v91, 0, v96
	v_mul_f32_e32 v96, v92, v92
	v_max_f32_e32 v92, 0, v97
	v_max_f32_e32 v93, 0, v93
	v_pk_mul_f32 v[84:85], v[84:85], v[100:101] op_sel_hi:[1,0]
	v_pk_mul_f32 v[82:83], v[82:83], v[100:101] op_sel_hi:[1,0]
	v_mul_f32_e32 v94, v94, v94
	v_mul_f32_e32 v91, v91, v91
	v_mul_f32_e32 v92, v92, v92
	v_mul_f32_e32 v93, v93, v93
	v_cvt_pk_bf16_f32 v90, v94, v90
	v_pk_mul_f32 v[88:89], v[88:89], v[100:101] op_sel_hi:[1,0]
	v_pk_mul_f32 v[86:87], v[86:87], v[100:101] op_sel_hi:[1,0]
	v_max_f32_e32 v82, 0, v82
	v_max_f32_e32 v83, 0, v83
	v_max_f32_e32 v84, 0, v84
	v_cvt_pk_bf16_f32 v91, v91, v92
	v_cvt_pk_bf16_f32 v92, v101, v95
	v_cvt_pk_bf16_f32 v93, v96, v93
	global_store_dwordx4 v[98:99], v[90:93], off
	v_max_f32_e32 v86, 0, v86
	v_max_f32_e32 v85, 0, v85
	v_mul_f32_e32 v90, v82, v82
	v_max_f32_e32 v82, 0, v87
	v_mul_f32_e32 v87, v83, v83
	v_max_f32_e32 v83, 0, v88
	v_mul_f32_e32 v88, v84, v84
	v_max_f32_e32 v84, 0, v89
	v_mul_f32_e32 v82, v82, v82
	v_mul_f32_e32 v83, v83, v83
	v_mul_f32_e32 v84, v84, v84
	v_mul_f32_e32 v86, v86, v86
	v_mul_f32_e32 v85, v85, v85
	v_cvt_pk_bf16_f32 v82, v86, v82
	v_cvt_pk_bf16_f32 v83, v83, v84
	v_cvt_pk_bf16_f32 v84, v90, v87
	s_and_b64 vcc, exec, s[40:41]
	v_cvt_pk_bf16_f32 v85, v88, v85
	global_store_dwordx4 v[98:99], v[82:85], off offset:256
	s_cbranch_vccnz .LBB0_725
	s_nop 1
	v_mov_b32_e32 v84, v217
	s_mov_b64 s[8:9], 0

.LBB0_727:
	v_fmamk_f32 v84, v84, 0x3a000000, v205
	v_mul_f32_e32 v85, 0x4b800000, v84
	v_cmp_gt_f32_e32 vcc, s12, v84
	v_lshlrev_b64 v[82:83], 14, v[82:83]
	v_lshl_add_u64 v[82:83], s[10:11], 0, v[82:83]
	v_cndmask_b32_e32 v84, v84, v85, vcc
	v_rsq_f32_e32 v84, v84
	v_lshl_add_u64 v[82:83], v[148:149], 1, v[82:83]
	s_mov_b64 s[8:9], -1
	v_mul_f32_e32 v85, 0x45800000, v84
	v_cndmask_b32_e32 v84, v84, v85, vcc
	v_pk_mul_f32 v[74:75], v[74:75], v[84:85] op_sel_hi:[1,0]
	v_pk_mul_f32 v[78:79], v[78:79], v[84:85] op_sel_hi:[1,0]
	v_pk_mul_f32 v[76:77], v[76:77], v[84:85] op_sel_hi:[1,0]
	v_max_f32_e32 v74, 0, v74
	v_pk_mul_f32 v[80:81], v[80:81], v[84:85] op_sel_hi:[1,0]
	v_mul_f32_e32 v85, v74, v74
	v_max_f32_e32 v74, 0, v79
	v_max_f32_e32 v75, 0, v75
	v_max_f32_e32 v76, 0, v76
	v_max_f32_e32 v78, 0, v78
	v_mul_f32_e32 v74, v74, v74
	v_mul_f32_e32 v79, v75, v75
	v_max_f32_e32 v75, 0, v80
	v_mul_f32_e32 v80, v76, v76
	v_max_f32_e32 v76, 0, v81
	v_max_f32_e32 v77, 0, v77
	v_pk_mul_f32 v[68:69], v[68:69], v[84:85] op_sel_hi:[1,0]
	v_pk_mul_f32 v[66:67], v[66:67], v[84:85] op_sel_hi:[1,0]
	v_mul_f32_e32 v78, v78, v78
	v_mul_f32_e32 v75, v75, v75
	v_mul_f32_e32 v76, v76, v76
	v_mul_f32_e32 v77, v77, v77
	v_cvt_pk_bf16_f32 v74, v78, v74
	v_pk_mul_f32 v[72:73], v[72:73], v[84:85] op_sel_hi:[1,0]
	v_pk_mul_f32 v[70:71], v[70:71], v[84:85] op_sel_hi:[1,0]
	v_max_f32_e32 v66, 0, v66
	v_max_f32_e32 v67, 0, v67
	v_max_f32_e32 v68, 0, v68
	v_cvt_pk_bf16_f32 v75, v75, v76
	v_cvt_pk_bf16_f32 v76, v85, v79
	v_cvt_pk_bf16_f32 v77, v80, v77
	global_store_dwordx4 v[82:83], v[74:77], off
	v_max_f32_e32 v70, 0, v70
	v_max_f32_e32 v69, 0, v69
	v_mul_f32_e32 v74, v66, v66
	v_max_f32_e32 v66, 0, v71
	v_mul_f32_e32 v71, v67, v67
	v_max_f32_e32 v67, 0, v72
	v_mul_f32_e32 v72, v68, v68
	v_max_f32_e32 v68, 0, v73
	v_mul_f32_e32 v66, v66, v66
	v_mul_f32_e32 v67, v67, v67
	v_mul_f32_e32 v68, v68, v68
	v_mul_f32_e32 v70, v70, v70
	v_mul_f32_e32 v69, v69, v69
	v_cvt_pk_bf16_f32 v66, v70, v66
	v_cvt_pk_bf16_f32 v67, v67, v68
	v_cvt_pk_bf16_f32 v68, v74, v71
	s_and_b64 vcc, exec, s[40:41]
	v_cvt_pk_bf16_f32 v69, v72, v69
	global_store_dwordx4 v[82:83], v[66:69], off offset:256
	s_cbranch_vccnz .LBB0_729
	s_nop 1
	v_mov_b32_e32 v68, v218
	s_mov_b64 s[8:9], 0

.LBB0_731:
	v_fmamk_f32 v68, v68, 0x3a000000, v205
	v_mul_f32_e32 v69, 0x4b800000, v68
	v_cmp_gt_f32_e32 vcc, s12, v68
	v_lshlrev_b64 v[66:67], 14, v[66:67]
	v_lshl_add_u64 v[66:67], s[10:11], 0, v[66:67]
	v_cndmask_b32_e32 v68, v68, v69, vcc
	v_rsq_f32_e32 v68, v68
	v_lshl_add_u64 v[66:67], v[148:149], 1, v[66:67]
	s_mov_b64 s[8:9], -1
	v_mul_f32_e32 v69, 0x45800000, v68
	v_cndmask_b32_e32 v68, v68, v69, vcc
	v_pk_mul_f32 v[58:59], v[58:59], v[68:69] op_sel_hi:[1,0]
	v_pk_mul_f32 v[62:63], v[62:63], v[68:69] op_sel_hi:[1,0]
	v_pk_mul_f32 v[60:61], v[60:61], v[68:69] op_sel_hi:[1,0]
	v_max_f32_e32 v58, 0, v58
	v_pk_mul_f32 v[64:65], v[64:65], v[68:69] op_sel_hi:[1,0]
	v_mul_f32_e32 v69, v58, v58
	v_max_f32_e32 v58, 0, v63
	v_max_f32_e32 v59, 0, v59
	v_max_f32_e32 v60, 0, v60
	v_max_f32_e32 v62, 0, v62
	v_mul_f32_e32 v58, v58, v58
	v_mul_f32_e32 v63, v59, v59
	v_max_f32_e32 v59, 0, v64
	v_mul_f32_e32 v64, v60, v60
	v_max_f32_e32 v60, 0, v65
	v_max_f32_e32 v61, 0, v61
	v_pk_mul_f32 v[52:53], v[52:53], v[68:69] op_sel_hi:[1,0]
	v_pk_mul_f32 v[50:51], v[50:51], v[68:69] op_sel_hi:[1,0]
	v_mul_f32_e32 v62, v62, v62
	v_mul_f32_e32 v59, v59, v59
	v_mul_f32_e32 v60, v60, v60
	v_mul_f32_e32 v61, v61, v61
	v_cvt_pk_bf16_f32 v58, v62, v58
	v_pk_mul_f32 v[56:57], v[56:57], v[68:69] op_sel_hi:[1,0]
	v_pk_mul_f32 v[54:55], v[54:55], v[68:69] op_sel_hi:[1,0]
	v_max_f32_e32 v50, 0, v50
	v_max_f32_e32 v51, 0, v51
	v_max_f32_e32 v52, 0, v52
	v_cvt_pk_bf16_f32 v59, v59, v60
	v_cvt_pk_bf16_f32 v60, v69, v63
	v_cvt_pk_bf16_f32 v61, v64, v61
	global_store_dwordx4 v[66:67], v[58:61], off
	v_max_f32_e32 v54, 0, v54
	v_max_f32_e32 v53, 0, v53
	v_mul_f32_e32 v58, v50, v50
	v_max_f32_e32 v50, 0, v55
	v_mul_f32_e32 v55, v51, v51
	v_max_f32_e32 v51, 0, v56
	v_mul_f32_e32 v56, v52, v52
	v_max_f32_e32 v52, 0, v57
	v_mul_f32_e32 v50, v50, v50
	v_mul_f32_e32 v51, v51, v51
	v_mul_f32_e32 v52, v52, v52
	v_mul_f32_e32 v54, v54, v54
	v_mul_f32_e32 v53, v53, v53
	v_cvt_pk_bf16_f32 v50, v54, v50
	v_cvt_pk_bf16_f32 v51, v51, v52
	v_cvt_pk_bf16_f32 v52, v58, v55
	s_and_b64 vcc, exec, s[40:41]
	v_cvt_pk_bf16_f32 v53, v56, v53
	global_store_dwordx4 v[66:67], v[50:53], off offset:256
	s_cbranch_vccnz .LBB0_733
	s_nop 1
	v_mov_b32_e32 v52, v219
	s_mov_b64 s[8:9], 0

.LBB0_735:
	v_fmamk_f32 v52, v52, 0x3a000000, v205
	v_mul_f32_e32 v53, 0x4b800000, v52
	v_cmp_gt_f32_e32 vcc, s12, v52
	v_lshlrev_b64 v[50:51], 14, v[50:51]
	v_lshl_add_u64 v[50:51], s[10:11], 0, v[50:51]
	v_cndmask_b32_e32 v52, v52, v53, vcc
	v_rsq_f32_e32 v52, v52
	v_lshl_add_u64 v[50:51], v[148:149], 1, v[50:51]
	s_mov_b64 s[8:9], -1
	v_mul_f32_e32 v53, 0x45800000, v52
	v_cndmask_b32_e32 v52, v52, v53, vcc
	v_pk_mul_f32 v[42:43], v[42:43], v[52:53] op_sel_hi:[1,0]
	v_pk_mul_f32 v[46:47], v[46:47], v[52:53] op_sel_hi:[1,0]
	v_pk_mul_f32 v[44:45], v[44:45], v[52:53] op_sel_hi:[1,0]
	v_max_f32_e32 v42, 0, v42
	v_pk_mul_f32 v[48:49], v[48:49], v[52:53] op_sel_hi:[1,0]
	v_mul_f32_e32 v53, v42, v42
	v_max_f32_e32 v42, 0, v47
	v_max_f32_e32 v43, 0, v43
	v_max_f32_e32 v44, 0, v44
	v_max_f32_e32 v46, 0, v46
	v_mul_f32_e32 v42, v42, v42
	v_mul_f32_e32 v47, v43, v43
	v_max_f32_e32 v43, 0, v48
	v_mul_f32_e32 v48, v44, v44
	v_max_f32_e32 v44, 0, v49
	v_max_f32_e32 v45, 0, v45
	v_pk_mul_f32 v[36:37], v[36:37], v[52:53] op_sel_hi:[1,0]
	v_pk_mul_f32 v[34:35], v[34:35], v[52:53] op_sel_hi:[1,0]
	v_mul_f32_e32 v46, v46, v46
	v_mul_f32_e32 v43, v43, v43
	v_mul_f32_e32 v44, v44, v44
	v_mul_f32_e32 v45, v45, v45
	v_cvt_pk_bf16_f32 v42, v46, v42
	v_pk_mul_f32 v[40:41], v[40:41], v[52:53] op_sel_hi:[1,0]
	v_pk_mul_f32 v[38:39], v[38:39], v[52:53] op_sel_hi:[1,0]
	v_max_f32_e32 v34, 0, v34
	v_max_f32_e32 v35, 0, v35
	v_max_f32_e32 v36, 0, v36
	v_cvt_pk_bf16_f32 v43, v43, v44
	v_cvt_pk_bf16_f32 v44, v53, v47
	v_cvt_pk_bf16_f32 v45, v48, v45
	global_store_dwordx4 v[50:51], v[42:45], off
	v_max_f32_e32 v38, 0, v38
	v_max_f32_e32 v37, 0, v37
	v_mul_f32_e32 v42, v34, v34
	v_max_f32_e32 v34, 0, v39
	v_mul_f32_e32 v39, v35, v35
	v_max_f32_e32 v35, 0, v40
	v_mul_f32_e32 v40, v36, v36
	v_max_f32_e32 v36, 0, v41
	v_mul_f32_e32 v34, v34, v34
	v_mul_f32_e32 v35, v35, v35
	v_mul_f32_e32 v36, v36, v36
	v_mul_f32_e32 v38, v38, v38
	v_mul_f32_e32 v37, v37, v37
	v_cvt_pk_bf16_f32 v34, v38, v34
	v_cvt_pk_bf16_f32 v35, v35, v36
	v_cvt_pk_bf16_f32 v36, v42, v39
	s_and_b64 vcc, exec, s[40:41]
	v_cvt_pk_bf16_f32 v37, v40, v37
	global_store_dwordx4 v[50:51], v[34:37], off offset:256
	s_cbranch_vccnz .LBB0_737
	s_nop 1
	v_mov_b32_e32 v36, v220
	s_mov_b64 s[8:9], 0

.LBB0_739:
	v_fmamk_f32 v36, v36, 0x3a000000, v205
	v_mul_f32_e32 v37, 0x4b800000, v36
	v_cmp_gt_f32_e32 vcc, s12, v36
	v_lshlrev_b64 v[34:35], 14, v[34:35]
	v_lshl_add_u64 v[34:35], s[10:11], 0, v[34:35]
	v_cndmask_b32_e32 v36, v36, v37, vcc
	v_rsq_f32_e32 v36, v36
	v_lshl_add_u64 v[34:35], v[148:149], 1, v[34:35]
	s_mov_b64 s[8:9], -1
	v_mul_f32_e32 v37, 0x45800000, v36
	v_cndmask_b32_e32 v36, v36, v37, vcc
	v_pk_mul_f32 v[26:27], v[26:27], v[36:37] op_sel_hi:[1,0]
	v_pk_mul_f32 v[30:31], v[30:31], v[36:37] op_sel_hi:[1,0]
	v_pk_mul_f32 v[28:29], v[28:29], v[36:37] op_sel_hi:[1,0]
	v_max_f32_e32 v26, 0, v26
	v_pk_mul_f32 v[32:33], v[32:33], v[36:37] op_sel_hi:[1,0]
	v_mul_f32_e32 v37, v26, v26
	v_max_f32_e32 v26, 0, v31
	v_max_f32_e32 v27, 0, v27
	v_max_f32_e32 v28, 0, v28
	v_max_f32_e32 v30, 0, v30
	v_mul_f32_e32 v26, v26, v26
	v_mul_f32_e32 v31, v27, v27
	v_max_f32_e32 v27, 0, v32
	v_mul_f32_e32 v32, v28, v28
	v_max_f32_e32 v28, 0, v33
	v_max_f32_e32 v29, 0, v29
	v_pk_mul_f32 v[20:21], v[20:21], v[36:37] op_sel_hi:[1,0]
	v_pk_mul_f32 v[18:19], v[18:19], v[36:37] op_sel_hi:[1,0]
	v_mul_f32_e32 v30, v30, v30
	v_mul_f32_e32 v27, v27, v27
	v_mul_f32_e32 v28, v28, v28
	v_mul_f32_e32 v29, v29, v29
	v_cvt_pk_bf16_f32 v26, v30, v26
	v_pk_mul_f32 v[24:25], v[24:25], v[36:37] op_sel_hi:[1,0]
	v_pk_mul_f32 v[22:23], v[22:23], v[36:37] op_sel_hi:[1,0]
	v_max_f32_e32 v18, 0, v18
	v_max_f32_e32 v19, 0, v19
	v_max_f32_e32 v20, 0, v20
	v_cvt_pk_bf16_f32 v27, v27, v28
	v_cvt_pk_bf16_f32 v28, v37, v31
	v_cvt_pk_bf16_f32 v29, v32, v29
	global_store_dwordx4 v[34:35], v[26:29], off
	v_max_f32_e32 v22, 0, v22
	v_max_f32_e32 v21, 0, v21
	v_mul_f32_e32 v26, v18, v18
	v_max_f32_e32 v18, 0, v23
	v_mul_f32_e32 v23, v19, v19
	v_max_f32_e32 v19, 0, v24
	v_mul_f32_e32 v24, v20, v20
	v_max_f32_e32 v20, 0, v25
	v_mul_f32_e32 v18, v18, v18
	v_mul_f32_e32 v19, v19, v19
	v_mul_f32_e32 v20, v20, v20
	v_mul_f32_e32 v22, v22, v22
	v_mul_f32_e32 v21, v21, v21
	v_cvt_pk_bf16_f32 v18, v22, v18
	v_cvt_pk_bf16_f32 v19, v19, v20
	v_cvt_pk_bf16_f32 v20, v26, v23
	s_and_b64 vcc, exec, s[40:41]
	v_cvt_pk_bf16_f32 v21, v24, v21
	global_store_dwordx4 v[34:35], v[18:21], off offset:256
	s_cbranch_vccnz .LBB0_741
	s_nop 1
	v_mov_b32_e32 v20, v221
	s_mov_b64 s[8:9], 0

.LBB0_743:
	v_fmamk_f32 v20, v20, 0x3a000000, v205
	v_mul_f32_e32 v21, 0x4b800000, v20
	v_cmp_gt_f32_e32 vcc, s12, v20
	v_lshlrev_b64 v[18:19], 14, v[18:19]
	v_lshl_add_u64 v[18:19], s[10:11], 0, v[18:19]
	v_cndmask_b32_e32 v20, v20, v21, vcc
	v_rsq_f32_e32 v20, v20
	v_lshl_add_u64 v[18:19], v[148:149], 1, v[18:19]
	s_mov_b64 s[8:9], -1
	v_mul_f32_e32 v21, 0x45800000, v20
	v_cndmask_b32_e32 v20, v20, v21, vcc
	v_pk_mul_f32 v[10:11], v[10:11], v[20:21] op_sel_hi:[1,0]
	v_pk_mul_f32 v[14:15], v[14:15], v[20:21] op_sel_hi:[1,0]
	v_pk_mul_f32 v[12:13], v[12:13], v[20:21] op_sel_hi:[1,0]
	v_max_f32_e32 v10, 0, v10
	v_pk_mul_f32 v[16:17], v[16:17], v[20:21] op_sel_hi:[1,0]
	v_mul_f32_e32 v21, v10, v10
	v_max_f32_e32 v10, 0, v15
	v_max_f32_e32 v11, 0, v11
	v_max_f32_e32 v12, 0, v12
	v_max_f32_e32 v14, 0, v14
	v_mul_f32_e32 v10, v10, v10
	v_mul_f32_e32 v15, v11, v11
	v_max_f32_e32 v11, 0, v16
	v_mul_f32_e32 v16, v12, v12
	v_max_f32_e32 v12, 0, v17
	v_max_f32_e32 v13, 0, v13
	v_pk_mul_f32 v[4:5], v[4:5], v[20:21] op_sel_hi:[1,0]
	v_pk_mul_f32 v[2:3], v[2:3], v[20:21] op_sel_hi:[1,0]
	v_mul_f32_e32 v14, v14, v14
	v_mul_f32_e32 v11, v11, v11
	v_mul_f32_e32 v12, v12, v12
	v_mul_f32_e32 v13, v13, v13
	v_cvt_pk_bf16_f32 v10, v14, v10
	v_pk_mul_f32 v[8:9], v[8:9], v[20:21] op_sel_hi:[1,0]
	v_pk_mul_f32 v[6:7], v[6:7], v[20:21] op_sel_hi:[1,0]
	v_max_f32_e32 v2, 0, v2
	v_max_f32_e32 v3, 0, v3
	v_max_f32_e32 v4, 0, v4
	v_cvt_pk_bf16_f32 v11, v11, v12
	v_cvt_pk_bf16_f32 v12, v21, v15
	v_cvt_pk_bf16_f32 v13, v16, v13
	global_store_dwordx4 v[18:19], v[10:13], off
	v_max_f32_e32 v5, 0, v5
	v_max_f32_e32 v6, 0, v6
	v_mul_f32_e32 v10, v2, v2
	v_max_f32_e32 v2, 0, v7
	v_mul_f32_e32 v7, v3, v3
	v_max_f32_e32 v3, 0, v8
	v_mul_f32_e32 v8, v4, v4
	v_max_f32_e32 v4, 0, v9
	v_mul_f32_e32 v2, v2, v2
	v_mul_f32_e32 v3, v3, v3
	v_mul_f32_e32 v4, v4, v4
	v_mul_f32_e32 v5, v5, v5
	s_andn2_b64 vcc, exec, s[38:39]
	v_mul_f32_e32 v6, v6, v6
	v_cvt_pk_bf16_f32 v2, v6, v2
	v_cvt_pk_bf16_f32 v3, v3, v4
	v_cvt_pk_bf16_f32 v4, v10, v7
	v_cvt_pk_bf16_f32 v5, v8, v5
	global_store_dwordx4 v[18:19], v[2:5], off offset:256
	s_cbranch_vccnz .LBB0_704
	s_andn2_b64 vcc, exec, s[4:5]
	s_cbranch_vccnz .LBB0_703
	s_barrier
	s_branch .LBB0_703
